# gate/up GEMM last round: each 6th-round tile is shared by two workgroups (the formerly idle one computes the other 128-row accumulator group); MFMAs and stores of the foreign half skipped
# speedup vs baseline: 1.0005x; 1.0005x over previous
.LBB0_35:
	v_readlane_b32 s36, v252, 58
	s_lshl_b32 s7, s7, 5
	v_mov_b32_e32 v1, v181
	v_readlane_b32 s37, v252, 59
	s_and_b32 s7, s7, 0x60
	s_add_i32 m0, s51, 0x18000
	v_lshl_add_u64 v[8:9], v[22:23], 0, s[94:95]
	v_lshl_add_u64 v[4:5], s[36:37], 0, v[0:1]
	v_mov_b32_e32 v133, v181
	s_lshl_b32 s15, s6, 13
	s_lshl_b32 s16, s7, 7
	s_waitcnt vmcnt(2)
	s_barrier
	global_load_lds_dwordx4 v[8:9], off
	v_lshl_add_u64 v[8:9], v[20:21], 0, s[94:95]
	s_add_i32 m0, s51, 0x1a000
	s_add_i32 s55, s51, 0x8000
	s_add_i32 s58, s51, 0xa000
	v_lshl_add_u64 v[6:7], s[36:37], 0, v[132:133]
	global_load_lds_dwordx4 v[8:9], off
	v_lshl_add_u64 v[4:5], v[4:5], 0, s[94:95]
	s_mov_b32 m0, s55
	s_add_u32 s10, s44, 0x40080
	global_load_lds_dwordx4 v[4:5], off
	v_lshl_add_u64 v[4:5], v[6:7], 0, s[94:95]
	s_mov_b32 m0, s58
	s_addc_u32 s11, s45, 0
	global_load_lds_dwordx4 v[4:5], off
	s_add_i32 m0, s51, 0x1c000
	v_lshl_add_u64 v[4:5], s[10:11], 0, v[180:181]
	global_load_lds_dwordx4 v[4:5], off
	v_lshl_add_u64 v[4:5], s[10:11], 0, v[134:135]
	s_add_i32 m0, s51, 0x1e000
	v_mov_b32_e32 v137, v181
	global_load_lds_dwordx4 v[4:5], off
	v_and_b32_e32 v4, 15, v24
	v_lshrrev_b32_e32 v5, 1, v24
	v_lshl_or_b32 v3, s6, 6, v4
	v_and_b32_e32 v5, 24, v5
	s_lshl_b32 s6, s6, 8
	v_lshlrev_b32_e32 v6, 1, v5
	s_add_i32 s6, s6, 0
	v_lshl_or_b32 v6, v4, 6, v6
	v_lshlrev_b32_e32 v4, 2, v4
	s_add_i32 s6, s6, 0x22000
	v_and_b32_e32 v7, 32, v4
	v_add_u32_e32 v143, s6, v4
	v_lshlrev_b32_e32 v4, 14, v25
	v_and_b32_e32 v4, 0xffff8000, v4
	v_or_b32_e32 v144, s7, v5
	v_lshl_add_u32 v4, v26, 11, v4
	v_and_b32_e32 v5, 1, v25
	v_lshl_or_b32 v4, v5, 6, v4
	v_lshl_add_u32 v136, v27, 1, v4
	v_lshlrev_b32_e32 v4, 14, v28
	v_and_b32_e32 v4, 0xffff8000, v4
	s_waitcnt vmcnt(6)
	v_lshl_add_u32 v4, v29, 11, v4
	v_and_b32_e32 v5, 1, v28
	v_bitop3_b32 v8, v6, s15, v7 bitop3:0xde
	s_cmpk_lt_u32 s14, 0x100
	v_lshl_or_b32 v4, v5, 6, v4
	v_readlane_b32 s6, v252, 56
	v_bitop3_b32 v142, v6, s16, v7 bitop3:0xde
	s_cselect_b64 s[10:11], -1, 0
	v_lshl_add_u32 v138, v30, 1, v4
	v_mov_b32_e32 v139, v181
	s_mov_b32 s59, 0
	v_add_u32_e32 v145, 0, v8
	s_mov_b32 s64, s6
	v_readlane_b32 s65, v252, 53
	s_barrier
	v_readlane_b32 s7, v252, 57
	s_mov_b32 s100, 0
	s_mov_b32 s101, 0
	s_branch .LBB0_38

.LBB0_38:
	s_add_i32 s59, s59, 1
	s_mul_i32 s6, s59, s93
	s_mul_hi_u32 s7, s59, s33
	s_add_i32 s7, s7, s6
	s_mul_i32 s6, s59, s33
	s_add_u32 s18, s6, s2
	s_addc_u32 s19, s7, s3
	s_mov_b32 s100, s101
	s_mov_b32 s101, 0
	s_cmp_lg_u32 s59, 5
	s_cbranch_scc1 .Lht_d0
	s_cmp_eq_u32 s22, 1
	s_cbranch_scc1 .Lht_d0
	s_mov_b32 s101, 1
	s_cmp_lt_u32 s18, 0x580
	s_cbranch_scc1 .Lht_d0
	s_sub_u32 s18, s18, 0x80
	s_mov_b32 s101, 2
.Lht_d0:
	v_mov_b64_e32 v[4:5], 0x580
	v_cmp_lt_i64_e64 s[6:7], s[18:19], v[4:5]
	v_mov_b64_e32 v[4:5], 0x57f
	v_cmp_gt_i64_e32 vcc, s[18:19], v[4:5]
	s_cbranch_vccnz .LBB0_40
	s_ashr_i32 s14, s18, 31
	s_lshr_b32 s14, s14, 29
	s_add_i32 s14, s18, s14
	s_ashr_i32 s15, s14, 3
	s_and_b32 s14, s14, -8
	s_sub_i32 s14, s18, s14
	s_cmp_lt_i32 s14, 0
	s_cselect_b32 s16, s1, 0xb0
	s_mul_i32 s14, s14, s16
	s_add_i32 s14, s14, s15
	s_mul_hi_i32 s15, s14, 0x2e8ba2e9
	s_lshr_b32 s16, s15, 31
	s_ashr_i32 s15, s15, 5
	s_add_i32 s15, s15, s16
	s_lshl_b32 s16, s15, 3
	s_sub_i32 s17, 64, s16
	s_min_i32 s17, s17, 8
	s_abs_i32 s18, s17
	v_cvt_f32_u32_e32 v4, s18
	s_sub_i32 s26, 0, s18
	s_mulk_i32 s15, 0xb0
	s_sub_i32 s15, s14, s15
	v_rcp_iflag_f32_e32 v4, v4
	s_abs_i32 s14, s15
	s_xor_b32 s19, s15, s17
	s_ashr_i32 s19, s19, 31
	v_mul_f32_e32 v4, 0x4f7ffffe, v4
	v_cvt_u32_f32_e32 v4, v4
	s_nop 0
	v_readfirstlane_b32 s27, v4
	s_mul_i32 s26, s26, s27
	s_mul_hi_u32 s26, s27, s26
	s_add_i32 s27, s27, s26
	s_mul_hi_u32 s26, s14, s27
	s_mul_i32 s27, s26, s18
	s_sub_i32 s14, s14, s27
	s_add_i32 s40, s26, 1
	s_sub_i32 s27, s14, s18
	s_cmp_ge_u32 s14, s18
	s_cselect_b32 s26, s40, s26
	s_cselect_b32 s14, s27, s14
	s_add_i32 s27, s26, 1
	s_cmp_ge_u32 s14, s18
	s_cselect_b32 s14, s27, s26
	s_xor_b32 s14, s14, s19
	s_sub_i32 s14, s14, s19
	s_mul_i32 s17, s14, s17
	s_sub_i32 s15, s15, s17
	s_add_i32 s16, s16, s15

.LBB0_41:
	s_add_u32 s40, s36, 0xfffc0080
	s_addc_u32 s41, s37, -1
	s_add_i32 s97, 0, 0x10000
	s_cmp_eq_u32 s90, 12
	s_cselect_b32 s47, s17, s41
	s_cselect_b32 s46, s68, s40
	v_add_u32_e32 v140, s97, v142
	s_cselect_b32 s45, s15, s89
	s_cselect_b32 s44, s69, s88
	s_add_i32 s40, 0, 0x14000
	ds_read_b128 v[146:149], v140
	ds_read_b128 v[150:153], v140 offset:1024
	ds_read_b128 v[154:157], v140 offset:2048
	ds_read_b128 v[158:161], v140 offset:3072
	v_add_u32_e32 v140, s40, v142
	ds_read_b128 v[162:165], v140
	ds_read_b128 v[166:169], v140 offset:1024
	ds_read_b128 v[170:173], v140 offset:2048
	ds_read_b128 v[174:177], v140 offset:3072
	v_lshl_add_u64 v[140:141], s[36:37], 0, v[136:137]
	s_add_i32 m0, s51, 0xc000
	ds_read_b128 v[190:193], v145
	ds_read_b128 v[194:197], v145 offset:1024
	ds_read_b128 v[198:201], v145 offset:2048
	ds_read_b128 v[202:205], v145 offset:3072
	ds_read_b128 v[206:209], v145 offset:4096
	ds_read_b128 v[228:231], v145 offset:5120
	ds_read_b128 v[232:235], v145 offset:6144
	ds_read_b128 v[236:239], v145 offset:7168
	global_load_lds_dwordx4 v[140:141], off
	v_lshl_add_u64 v[140:141], s[36:37], 0, v[138:139]
	s_add_i32 m0, s51, 0xe000
	s_nop 0
	global_load_lds_dwordx4 v[140:141], off
	s_waitcnt vmcnt(8)
	s_waitcnt lgkmcnt(0)
	s_barrier
	s_setprio 1
	s_waitcnt lgkmcnt(0)
	s_cmp_eq_u32 s100, 2
	s_cbranch_scc1 .Lht_mma0
	v_mfma_f32_16x16x32_bf16 v[124:127], v[146:149], v[190:193], v[124:127]
	v_mfma_f32_16x16x32_bf16 v[116:119], v[154:157], v[190:193], v[116:119]
	v_mfma_f32_16x16x32_bf16 v[108:111], v[146:149], v[198:201], v[108:111]
	v_mfma_f32_16x16x32_bf16 v[100:103], v[154:157], v[198:201], v[100:103]
	v_mfma_f32_16x16x32_bf16 v[92:95], v[146:149], v[206:209], v[92:95]
	v_mfma_f32_16x16x32_bf16 v[84:87], v[154:157], v[206:209], v[84:87]
	v_mfma_f32_16x16x32_bf16 v[76:79], v[146:149], v[232:235], v[76:79]
	v_mfma_f32_16x16x32_bf16 v[68:71], v[154:157], v[232:235], v[68:71]
	v_mfma_f32_16x16x32_bf16 v[124:127], v[150:153], v[194:197], v[124:127]
	v_mfma_f32_16x16x32_bf16 v[116:119], v[158:161], v[194:197], v[116:119]
	v_mfma_f32_16x16x32_bf16 v[108:111], v[150:153], v[202:205], v[108:111]
	v_mfma_f32_16x16x32_bf16 v[100:103], v[158:161], v[202:205], v[100:103]
	v_mfma_f32_16x16x32_bf16 v[92:95], v[150:153], v[228:231], v[92:95]
	v_mfma_f32_16x16x32_bf16 v[84:87], v[158:161], v[228:231], v[84:87]
	v_mfma_f32_16x16x32_bf16 v[76:79], v[150:153], v[236:239], v[76:79]
	v_mfma_f32_16x16x32_bf16 v[68:71], v[158:161], v[236:239], v[68:71]
	s_setprio 0
	s_setprio 1
	v_mfma_f32_16x16x32_bf16 v[128:131], v[162:165], v[190:193], v[128:131]
	v_mfma_f32_16x16x32_bf16 v[120:123], v[170:173], v[190:193], v[120:123]
	v_mfma_f32_16x16x32_bf16 v[112:115], v[162:165], v[198:201], v[112:115]
	v_mfma_f32_16x16x32_bf16 v[104:107], v[170:173], v[198:201], v[104:107]
	v_mfma_f32_16x16x32_bf16 v[96:99], v[162:165], v[206:209], v[96:99]
	v_mfma_f32_16x16x32_bf16 v[88:91], v[170:173], v[206:209], v[88:91]
	v_mfma_f32_16x16x32_bf16 v[80:83], v[162:165], v[232:235], v[80:83]
	v_mfma_f32_16x16x32_bf16 v[72:75], v[170:173], v[232:235], v[72:75]
	v_mfma_f32_16x16x32_bf16 v[128:131], v[166:169], v[194:197], v[128:131]
	v_mfma_f32_16x16x32_bf16 v[120:123], v[174:177], v[194:197], v[120:123]
	v_mfma_f32_16x16x32_bf16 v[112:115], v[166:169], v[202:205], v[112:115]
	v_mfma_f32_16x16x32_bf16 v[104:107], v[174:177], v[202:205], v[104:107]
	v_mfma_f32_16x16x32_bf16 v[96:99], v[166:169], v[228:231], v[96:99]
	v_mfma_f32_16x16x32_bf16 v[88:91], v[174:177], v[228:231], v[88:91]
	v_mfma_f32_16x16x32_bf16 v[80:83], v[166:169], v[236:239], v[80:83]
	v_mfma_f32_16x16x32_bf16 v[72:75], v[174:177], v[236:239], v[72:75]
.Lht_mma0:
	s_setprio 0
	s_barrier
	s_add_i32 s41, s97, s50
	v_lshl_add_u64 v[140:141], s[44:45], 0, v[180:181]
	s_mov_b32 m0, s41
	ds_read_b128 v[190:193], v145 offset:16384
	ds_read_b128 v[194:197], v145 offset:17408
	ds_read_b128 v[198:201], v145 offset:18432
	ds_read_b128 v[202:205], v145 offset:19456
	ds_read_b128 v[206:209], v145 offset:20480
	ds_read_b128 v[228:231], v145 offset:21504
	ds_read_b128 v[232:235], v145 offset:22528
	ds_read_b128 v[236:239], v145 offset:23552
	global_load_lds_dwordx4 v[140:141], off
	s_add_i32 m0, s41, 0x2000
	s_add_u32 vcc_lo, s44, 0x40000
	v_lshl_add_u64 v[178:179], s[44:45], 0, v[134:135]
	s_addc_u32 vcc_hi, s45, 0
	s_add_i32 s40, s40, s50
	global_load_lds_dwordx4 v[178:179], off
	v_lshl_add_u64 v[210:211], vcc, 0, v[180:181]
	s_mov_b32 m0, s40
	v_lshl_add_u64 v[218:219], s[46:47], 0, v[132:133]
	global_load_lds_dwordx4 v[210:211], off
	v_lshl_add_u64 v[210:211], vcc, 0, v[134:135]
	s_add_i32 m0, s40, 0x2000
	s_nop 0
	global_load_lds_dwordx4 v[210:211], off
	v_lshl_add_u64 v[210:211], s[46:47], 0, v[0:1]
	s_mov_b32 m0, s51
	s_nop 0
	global_load_lds_dwordx4 v[210:211], off
	s_mov_b32 m0, s52
	s_nop 0
	global_load_lds_dwordx4 v[218:219], off
	s_waitcnt vmcnt(8)
	s_waitcnt lgkmcnt(0)
	s_barrier
	s_setprio 1
	s_waitcnt lgkmcnt(0)
	s_cmp_eq_u32 s100, 1
	s_cbranch_scc1 .Lht_mma1
	v_mfma_f32_16x16x32_bf16 v[60:63], v[146:149], v[190:193], v[60:63]
	v_mfma_f32_16x16x32_bf16 v[52:55], v[154:157], v[190:193], v[52:55]
	v_mfma_f32_16x16x32_bf16 v[44:47], v[146:149], v[198:201], v[44:47]
	v_mfma_f32_16x16x32_bf16 v[36:39], v[154:157], v[198:201], v[36:39]
	v_mfma_f32_16x16x32_bf16 v[28:31], v[146:149], v[206:209], v[28:31]
	v_mfma_f32_16x16x32_bf16 v[20:23], v[154:157], v[206:209], v[20:23]
	v_mfma_f32_16x16x32_bf16 v[12:15], v[146:149], v[232:235], v[12:15]
	v_mfma_f32_16x16x32_bf16 v[8:11], v[154:157], v[232:235], v[8:11]
	v_mfma_f32_16x16x32_bf16 v[60:63], v[150:153], v[194:197], v[60:63]
	v_mfma_f32_16x16x32_bf16 v[52:55], v[158:161], v[194:197], v[52:55]
	v_mfma_f32_16x16x32_bf16 v[44:47], v[150:153], v[202:205], v[44:47]
	v_mfma_f32_16x16x32_bf16 v[36:39], v[158:161], v[202:205], v[36:39]
	v_mfma_f32_16x16x32_bf16 v[28:31], v[150:153], v[228:231], v[28:31]
	v_mfma_f32_16x16x32_bf16 v[20:23], v[158:161], v[228:231], v[20:23]
	v_mfma_f32_16x16x32_bf16 v[12:15], v[150:153], v[236:239], v[12:15]
	v_mfma_f32_16x16x32_bf16 v[8:11], v[158:161], v[236:239], v[8:11]
	s_setprio 0
	s_setprio 1
	v_mfma_f32_16x16x32_bf16 v[64:67], v[162:165], v[190:193], v[64:67]
	v_mfma_f32_16x16x32_bf16 v[56:59], v[170:173], v[190:193], v[56:59]
	v_mfma_f32_16x16x32_bf16 v[48:51], v[162:165], v[198:201], v[48:51]
	v_mfma_f32_16x16x32_bf16 v[40:43], v[170:173], v[198:201], v[40:43]
	v_mfma_f32_16x16x32_bf16 v[32:35], v[162:165], v[206:209], v[32:35]
	v_mfma_f32_16x16x32_bf16 v[24:27], v[170:173], v[206:209], v[24:27]
	v_mfma_f32_16x16x32_bf16 v[16:19], v[162:165], v[232:235], v[16:19]
	v_mfma_f32_16x16x32_bf16 v[4:7], v[170:173], v[232:235], v[4:7]
	v_mfma_f32_16x16x32_bf16 v[64:67], v[166:169], v[194:197], v[64:67]
	v_mfma_f32_16x16x32_bf16 v[56:59], v[174:177], v[194:197], v[56:59]
	v_mfma_f32_16x16x32_bf16 v[48:51], v[166:169], v[202:205], v[48:51]
	v_mfma_f32_16x16x32_bf16 v[40:43], v[174:177], v[202:205], v[40:43]
	v_mfma_f32_16x16x32_bf16 v[32:35], v[166:169], v[228:231], v[32:35]
	v_mfma_f32_16x16x32_bf16 v[24:27], v[174:177], v[228:231], v[24:27]
	v_mfma_f32_16x16x32_bf16 v[16:19], v[166:169], v[236:239], v[16:19]
	v_mfma_f32_16x16x32_bf16 v[4:7], v[174:177], v[236:239], v[4:7]
.Lht_mma1:
	s_setprio 0
	s_barrier
	s_add_i32 s40, 0, 0x18000
	s_add_i32 s41, 0, 0x1c000
	v_add_u32_e32 v158, s40, v142
	v_add_u32_e32 v174, s41, v142
	ds_read_b128 v[146:149], v158
	ds_read_b128 v[150:153], v158 offset:1024
	ds_read_b128 v[154:157], v158 offset:2048
	ds_read_b128 v[158:161], v158 offset:3072
	ds_read_b128 v[162:165], v174
	ds_read_b128 v[166:169], v174 offset:1024
	ds_read_b128 v[170:173], v174 offset:2048
	ds_read_b128 v[174:177], v174 offset:3072
	s_add_u32 s46, s46, 0x40000
	s_addc_u32 s47, s47, 0
	s_mov_b32 m0, s53
	v_lshl_add_u64 v[220:221], s[46:47], 0, v[0:1]
	ds_read_b128 v[190:193], v145 offset:32768
	ds_read_b128 v[194:197], v145 offset:33792
	ds_read_b128 v[198:201], v145 offset:34816
	ds_read_b128 v[202:205], v145 offset:35840
	ds_read_b128 v[206:209], v145 offset:36864
	ds_read_b128 v[228:231], v145 offset:37888
	ds_read_b128 v[232:235], v145 offset:38912
	ds_read_b128 v[236:239], v145 offset:39936
	global_load_lds_dwordx4 v[220:221], off
	v_lshl_add_u64 v[220:221], s[46:47], 0, v[132:133]
	s_mov_b32 m0, s54
	s_nop 0
	global_load_lds_dwordx4 v[220:221], off
	s_waitcnt vmcnt(8)
	s_waitcnt lgkmcnt(0)
	s_barrier
	s_setprio 1
	s_waitcnt lgkmcnt(0)
	s_cmp_eq_u32 s100, 2
	s_cbranch_scc1 .Lht_mma2
	v_mfma_f32_16x16x32_bf16 v[124:127], v[146:149], v[190:193], v[124:127]
	v_mfma_f32_16x16x32_bf16 v[116:119], v[154:157], v[190:193], v[116:119]
	v_mfma_f32_16x16x32_bf16 v[108:111], v[146:149], v[198:201], v[108:111]
	v_mfma_f32_16x16x32_bf16 v[100:103], v[154:157], v[198:201], v[100:103]
	v_mfma_f32_16x16x32_bf16 v[92:95], v[146:149], v[206:209], v[92:95]
	v_mfma_f32_16x16x32_bf16 v[84:87], v[154:157], v[206:209], v[84:87]
	v_mfma_f32_16x16x32_bf16 v[76:79], v[146:149], v[232:235], v[76:79]
	v_mfma_f32_16x16x32_bf16 v[68:71], v[154:157], v[232:235], v[68:71]
	v_mfma_f32_16x16x32_bf16 v[124:127], v[150:153], v[194:197], v[124:127]
	v_mfma_f32_16x16x32_bf16 v[116:119], v[158:161], v[194:197], v[116:119]
	v_mfma_f32_16x16x32_bf16 v[108:111], v[150:153], v[202:205], v[108:111]
	v_mfma_f32_16x16x32_bf16 v[100:103], v[158:161], v[202:205], v[100:103]
	v_mfma_f32_16x16x32_bf16 v[92:95], v[150:153], v[228:231], v[92:95]
	v_mfma_f32_16x16x32_bf16 v[84:87], v[158:161], v[228:231], v[84:87]
	v_mfma_f32_16x16x32_bf16 v[76:79], v[150:153], v[236:239], v[76:79]
	v_mfma_f32_16x16x32_bf16 v[68:71], v[158:161], v[236:239], v[68:71]
	s_setprio 0
	s_setprio 1
	v_mfma_f32_16x16x32_bf16 v[128:131], v[162:165], v[190:193], v[128:131]
	v_mfma_f32_16x16x32_bf16 v[120:123], v[170:173], v[190:193], v[120:123]
	v_mfma_f32_16x16x32_bf16 v[112:115], v[162:165], v[198:201], v[112:115]
	v_mfma_f32_16x16x32_bf16 v[104:107], v[170:173], v[198:201], v[104:107]
	v_mfma_f32_16x16x32_bf16 v[96:99], v[162:165], v[206:209], v[96:99]
	v_mfma_f32_16x16x32_bf16 v[88:91], v[170:173], v[206:209], v[88:91]
	v_mfma_f32_16x16x32_bf16 v[80:83], v[162:165], v[232:235], v[80:83]
	v_mfma_f32_16x16x32_bf16 v[72:75], v[170:173], v[232:235], v[72:75]
	v_mfma_f32_16x16x32_bf16 v[128:131], v[166:169], v[194:197], v[128:131]
	v_mfma_f32_16x16x32_bf16 v[120:123], v[174:177], v[194:197], v[120:123]
	v_mfma_f32_16x16x32_bf16 v[112:115], v[166:169], v[202:205], v[112:115]
	v_mfma_f32_16x16x32_bf16 v[104:107], v[174:177], v[202:205], v[104:107]
	v_mfma_f32_16x16x32_bf16 v[96:99], v[166:169], v[228:231], v[96:99]
	v_mfma_f32_16x16x32_bf16 v[88:91], v[174:177], v[228:231], v[88:91]
	v_mfma_f32_16x16x32_bf16 v[80:83], v[166:169], v[236:239], v[80:83]
	v_mfma_f32_16x16x32_bf16 v[72:75], v[174:177], v[236:239], v[72:75]
.Lht_mma2:
	s_setprio 0
	s_barrier
	s_add_i32 s40, s40, s50
	v_lshl_add_u64 v[140:141], v[140:141], 0, s[94:95]
	s_mov_b32 m0, s40
	ds_read_b128 v[190:193], v145 offset:49152
	ds_read_b128 v[194:197], v145 offset:50176
	ds_read_b128 v[198:201], v145 offset:51200
	ds_read_b128 v[202:205], v145 offset:52224
	ds_read_b128 v[206:209], v145 offset:53248
	ds_read_b128 v[228:231], v145 offset:54272
	ds_read_b128 v[232:235], v145 offset:55296
	ds_read_b128 v[236:239], v145 offset:56320
	global_load_lds_dwordx4 v[140:141], off
	s_add_i32 m0, s40, 0x2000
	s_add_u32 s44, s44, 0x40080
	v_lshl_add_u64 v[140:141], v[178:179], 0, s[94:95]
	s_addc_u32 s45, s45, 0
	s_add_i32 s40, s41, s50
	global_load_lds_dwordx4 v[140:141], off
	v_lshl_add_u64 v[140:141], s[44:45], 0, v[180:181]
	s_mov_b32 m0, s40
	s_nop 0
	global_load_lds_dwordx4 v[140:141], off
	v_lshl_add_u64 v[140:141], s[44:45], 0, v[134:135]
	s_add_i32 m0, s40, 0x2000
	s_nop 0
	global_load_lds_dwordx4 v[140:141], off
	v_lshl_add_u64 v[140:141], v[210:211], 0, s[94:95]
	s_mov_b32 m0, s55
	s_nop 0
	global_load_lds_dwordx4 v[140:141], off
	v_lshl_add_u64 v[140:141], v[218:219], 0, s[94:95]
	s_mov_b32 m0, s58
	s_nop 0
	global_load_lds_dwordx4 v[140:141], off
	s_waitcnt vmcnt(8)
	s_waitcnt lgkmcnt(0)
	s_barrier
	s_setprio 1
	s_waitcnt lgkmcnt(0)
	s_cmp_eq_u32 s100, 1
	s_cbranch_scc1 .Lht_mma3
	v_mfma_f32_16x16x32_bf16 v[60:63], v[146:149], v[190:193], v[60:63]
	v_mfma_f32_16x16x32_bf16 v[52:55], v[154:157], v[190:193], v[52:55]
	v_mfma_f32_16x16x32_bf16 v[44:47], v[146:149], v[198:201], v[44:47]
	v_mfma_f32_16x16x32_bf16 v[36:39], v[154:157], v[198:201], v[36:39]
	v_mfma_f32_16x16x32_bf16 v[28:31], v[146:149], v[206:209], v[28:31]
	v_mfma_f32_16x16x32_bf16 v[20:23], v[154:157], v[206:209], v[20:23]
	v_mfma_f32_16x16x32_bf16 v[12:15], v[146:149], v[232:235], v[12:15]
	v_mfma_f32_16x16x32_bf16 v[8:11], v[154:157], v[232:235], v[8:11]
	v_mfma_f32_16x16x32_bf16 v[60:63], v[150:153], v[194:197], v[60:63]
	v_mfma_f32_16x16x32_bf16 v[52:55], v[158:161], v[194:197], v[52:55]
	v_mfma_f32_16x16x32_bf16 v[44:47], v[150:153], v[202:205], v[44:47]
	v_mfma_f32_16x16x32_bf16 v[36:39], v[158:161], v[202:205], v[36:39]
	v_mfma_f32_16x16x32_bf16 v[28:31], v[150:153], v[228:231], v[28:31]
	v_mfma_f32_16x16x32_bf16 v[20:23], v[158:161], v[228:231], v[20:23]
	v_mfma_f32_16x16x32_bf16 v[12:15], v[150:153], v[236:239], v[12:15]
	v_mfma_f32_16x16x32_bf16 v[8:11], v[158:161], v[236:239], v[8:11]
	s_setprio 0
	s_setprio 1
	v_mfma_f32_16x16x32_bf16 v[64:67], v[162:165], v[190:193], v[64:67]
	v_mfma_f32_16x16x32_bf16 v[56:59], v[170:173], v[190:193], v[56:59]
	v_mfma_f32_16x16x32_bf16 v[48:51], v[162:165], v[198:201], v[48:51]
	v_mfma_f32_16x16x32_bf16 v[40:43], v[170:173], v[198:201], v[40:43]
	v_mfma_f32_16x16x32_bf16 v[32:35], v[162:165], v[206:209], v[32:35]
	v_mfma_f32_16x16x32_bf16 v[24:27], v[170:173], v[206:209], v[24:27]
	v_mfma_f32_16x16x32_bf16 v[16:19], v[162:165], v[232:235], v[16:19]
	v_mfma_f32_16x16x32_bf16 v[4:7], v[170:173], v[232:235], v[4:7]
	v_mfma_f32_16x16x32_bf16 v[64:67], v[166:169], v[194:197], v[64:67]
	v_mfma_f32_16x16x32_bf16 v[56:59], v[174:177], v[194:197], v[56:59]
	v_mfma_f32_16x16x32_bf16 v[48:51], v[166:169], v[202:205], v[48:51]
	v_mfma_f32_16x16x32_bf16 v[40:43], v[174:177], v[202:205], v[40:43]
	v_mfma_f32_16x16x32_bf16 v[32:35], v[166:169], v[228:231], v[32:35]
	v_mfma_f32_16x16x32_bf16 v[24:27], v[174:177], v[228:231], v[24:27]
	v_mfma_f32_16x16x32_bf16 v[16:19], v[166:169], v[236:239], v[16:19]
	v_mfma_f32_16x16x32_bf16 v[4:7], v[174:177], v[236:239], v[4:7]
.Lht_mma3:
	s_setprio 0
	s_barrier
	s_add_i32 s90, s90, 2
	s_add_u32 s36, s36, 0x100
	s_addc_u32 s37, s37, 0
	s_add_u32 s88, s88, 0x100
	s_addc_u32 s89, s89, 0
	s_cmp_gt_u32 s90, 13
	s_cbranch_scc0 .LBB0_41
	s_and_b64 vcc, exec, s[10:11]
	s_cbranch_vccz .LBB0_44
	s_barrier
.LBB0_44:
	s_lshl_b32 s15, s64, 10
	s_and_b32 s15, s15, 0x1c00
	v_add_u32_e32 v147, s15, v143
	ds_read2_b32 v[154:155], v147 offset1:16
	ds_read2_b32 v[156:157], v147 offset0:32 offset1:48
	ds_read2_b32 v[158:159], v147 offset0:128 offset1:144
	s_nop 0
	v_pk_mul_f32 v[122:123], v[118:119], v[122:123]
	v_pk_mul_f32 v[130:131], v[126:127], v[130:131]
	v_lshl_add_u32 v146, s64, 8, v3
	v_lshl_or_b32 v140, s65, 7, v144
	s_nop 0
	s_waitcnt lgkmcnt(2)
	v_mul_f32_e32 v152, 0xbfb8aa3b, v154
	v_mul_f32_e32 v150, v124, v152
	v_mul_f32_e32 v151, v125, v152
	v_exp_f32_e32 v150, v150
	v_exp_f32_e32 v151, v151
	v_mul_f32_e32 v154, v154, v154
	v_pk_mul_f32 v[124:125], v[124:125], v[128:129]
	v_add_f32_e32 v150, 1.0, v150
	v_add_f32_e32 v151, 1.0, v151
	v_rcp_f32_e32 v150, v150
	v_rcp_f32_e32 v151, v151
	v_mul_f32_e32 v118, v118, v152
	v_mul_f32_e32 v119, v119, v152
	v_exp_f32_e32 v118, v118
	v_pk_mul_f32 v[128:129], v[154:155], v[150:151] op_sel_hi:[0,1]
	v_pk_mul_f32 v[124:125], v[124:125], v[128:129]
	v_mul_f32_e32 v128, v116, v152
	v_mul_f32_e32 v129, v117, v152
	v_exp_f32_e32 v128, v128
	v_exp_f32_e32 v129, v129
	v_exp_f32_e32 v119, v119
	v_mul_f32_e32 v126, v126, v152
	v_mul_f32_e32 v127, v127, v152
	v_exp_f32_e32 v126, v126
	v_exp_f32_e32 v127, v127
	v_add_f32_e32 v128, 1.0, v128
	v_add_f32_e32 v129, 1.0, v129
	v_rcp_f32_e32 v128, v128
	v_rcp_f32_e32 v129, v129
	v_add_f32_e32 v118, 1.0, v118
	v_add_f32_e32 v119, 1.0, v119
	v_rcp_f32_e32 v118, v118
	v_rcp_f32_e32 v119, v119
	v_add_f32_e32 v126, 1.0, v126
	v_add_f32_e32 v127, 1.0, v127
	v_rcp_f32_e32 v126, v126
	v_rcp_f32_e32 v127, v127
	v_pk_mul_f32 v[116:117], v[116:117], v[120:121]
	v_pk_mul_f32 v[120:121], v[154:155], v[128:129] op_sel_hi:[0,1]
	v_pk_mul_f32 v[116:117], v[116:117], v[120:121]
	v_pk_mul_f32 v[118:119], v[154:155], v[118:119] op_sel_hi:[0,1]
	v_pk_mul_f32 v[118:119], v[122:123], v[118:119]
	v_cvt_pk_bf16_f32 v122, v116, v117
	v_mov_b64_e32 v[116:117], s[4:5]
	s_ashr_i32 s15, s64, 3
	v_ashrrev_i32_e32 v141, 31, v140
	v_pk_mul_f32 v[126:127], v[154:155], v[126:127] op_sel_hi:[0,1]
	v_cvt_pk_bf16_f32 v123, v118, v119
	v_mad_i64_i32 v[118:119], s[36:37], v146, s35, v[116:117]
	v_pk_mul_f32 v[126:127], v[130:131], v[126:127]
	v_cvt_pk_bf16_f32 v120, v124, v125
	v_mad_i64_i32 v[124:125], s[36:37], s15, v215, v[118:119]
	v_lshlrev_b64 v[118:119], 1, v[140:141]
	v_cvt_pk_bf16_f32 v121, v126, v127
	v_lshl_add_u64 v[124:125], v[124:125], 0, v[118:119]
	s_cmp_eq_u32 s100, 2
	s_cbranch_scc1 .Lht_st0
	global_store_dwordx4 v[124:125], v[120:123], off
.Lht_st0:
	v_pk_mul_f32 v[114:115], v[110:111], v[114:115]
	v_pk_mul_f32 v[106:107], v[102:103], v[106:107]
	v_mul_f32_e32 v121, 0xbfb8aa3b, v155
	v_mul_f32_e32 v122, v108, v121
	v_mul_f32_e32 v123, v109, v121
	v_exp_f32_e32 v122, v122
	v_exp_f32_e32 v123, v123
	v_mul_f32_e32 v120, v155, v155
	v_pk_mul_f32 v[108:109], v[108:109], v[112:113]
	v_add_f32_e32 v122, 1.0, v122
	v_add_f32_e32 v123, 1.0, v123
	v_rcp_f32_e32 v122, v122
	v_rcp_f32_e32 v123, v123
	v_mul_f32_e32 v110, v110, v121
	v_mul_f32_e32 v111, v111, v121
	v_exp_f32_e32 v110, v110
	v_pk_mul_f32 v[112:113], v[120:121], v[122:123] op_sel_hi:[0,1]
	v_pk_mul_f32 v[108:109], v[108:109], v[112:113]
	v_mul_f32_e32 v112, v100, v121
	v_mul_f32_e32 v113, v101, v121
	v_exp_f32_e32 v112, v112
	v_exp_f32_e32 v113, v113
	v_pk_mul_f32 v[100:101], v[100:101], v[104:105]
	v_exp_f32_e32 v111, v111
	v_add_f32_e32 v112, 1.0, v112
	v_add_f32_e32 v113, 1.0, v113
	v_rcp_f32_e32 v112, v112
	v_rcp_f32_e32 v113, v113
	v_add_f32_e32 v110, 1.0, v110
	v_add_f32_e32 v111, 1.0, v111
	v_rcp_f32_e32 v110, v110
	v_pk_mul_f32 v[104:105], v[120:121], v[112:113] op_sel_hi:[0,1]
	v_pk_mul_f32 v[104:105], v[100:101], v[104:105]
	v_mul_f32_e32 v100, v102, v121
	v_mul_f32_e32 v101, v103, v121
	v_exp_f32_e32 v100, v100
	v_exp_f32_e32 v101, v101
	v_rcp_f32_e32 v111, v111
	v_or_b32_e32 v112, 16, v146
	v_add_f32_e32 v100, 1.0, v100
	v_add_f32_e32 v101, 1.0, v101
	v_rcp_f32_e32 v100, v100
	v_rcp_f32_e32 v101, v101
	v_pk_mul_f32 v[110:111], v[120:121], v[110:111] op_sel_hi:[0,1]
	v_cvt_pk_bf16_f32 v102, v104, v105
	v_mad_i64_i32 v[104:105], s[36:37], v112, s35, v[116:117]
	v_pk_mul_f32 v[100:101], v[120:121], v[100:101] op_sel_hi:[0,1]
	v_pk_mul_f32 v[110:111], v[114:115], v[110:111]
	v_pk_mul_f32 v[106:107], v[106:107], v[100:101]
	v_mad_i64_i32 v[104:105], s[36:37], s15, v215, v[104:105]
	v_cvt_pk_bf16_f32 v100, v108, v109
	v_cvt_pk_bf16_f32 v101, v110, v111
	v_cvt_pk_bf16_f32 v103, v106, v107
	v_lshl_add_u64 v[104:105], v[104:105], 0, v[118:119]
	s_cmp_eq_u32 s100, 2
	s_cbranch_scc1 .Lht_st1
	global_store_dwordx4 v[104:105], v[100:103], off
.Lht_st1:
	s_nop 0
	v_pk_mul_f32 v[98:99], v[94:95], v[98:99]
	v_pk_mul_f32 v[90:91], v[86:87], v[90:91]
	v_pk_mul_f32 v[82:83], v[78:79], v[82:83]
	v_pk_mul_f32 v[74:75], v[70:71], v[74:75]
	s_nop 0
	s_waitcnt lgkmcnt(1)
	v_mul_f32_e32 v104, 0xbfb8aa3b, v156
	v_mul_f32_e32 v102, v92, v104
	v_mul_f32_e32 v103, v93, v104
	v_exp_f32_e32 v102, v102
	v_exp_f32_e32 v103, v103
	v_mul_f32_e32 v156, v156, v156
	v_pk_mul_f32 v[92:93], v[92:93], v[96:97]
	v_add_f32_e32 v102, 1.0, v102
	v_add_f32_e32 v103, 1.0, v103
	v_rcp_f32_e32 v102, v102
	v_rcp_f32_e32 v103, v103
	v_mul_f32_e32 v94, v94, v104
	v_mul_f32_e32 v95, v95, v104
	v_exp_f32_e32 v94, v94
	v_pk_mul_f32 v[96:97], v[156:157], v[102:103] op_sel_hi:[0,1]
	v_pk_mul_f32 v[92:93], v[92:93], v[96:97]
	v_mul_f32_e32 v96, v84, v104
	v_mul_f32_e32 v97, v85, v104
	v_exp_f32_e32 v96, v96
	v_exp_f32_e32 v97, v97
	v_pk_mul_f32 v[84:85], v[84:85], v[88:89]
	v_exp_f32_e32 v95, v95
	v_add_f32_e32 v96, 1.0, v96
	v_add_f32_e32 v97, 1.0, v97
	v_rcp_f32_e32 v96, v96
	v_rcp_f32_e32 v97, v97
	v_add_f32_e32 v94, 1.0, v94
	v_add_f32_e32 v95, 1.0, v95
	v_rcp_f32_e32 v94, v94
	v_pk_mul_f32 v[88:89], v[156:157], v[96:97] op_sel_hi:[0,1]
	v_pk_mul_f32 v[88:89], v[84:85], v[88:89]
	v_mul_f32_e32 v84, v86, v104
	v_mul_f32_e32 v85, v87, v104
	v_exp_f32_e32 v84, v84
	v_exp_f32_e32 v85, v85
	v_rcp_f32_e32 v95, v95
	v_or_b32_e32 v96, 32, v146
	v_add_f32_e32 v84, 1.0, v84
	v_add_f32_e32 v85, 1.0, v85
	v_rcp_f32_e32 v84, v84
	v_rcp_f32_e32 v85, v85
	v_pk_mul_f32 v[94:95], v[156:157], v[94:95] op_sel_hi:[0,1]
	v_cvt_pk_bf16_f32 v86, v88, v89
	v_mad_i64_i32 v[88:89], s[36:37], v96, s35, v[116:117]
	v_pk_mul_f32 v[84:85], v[156:157], v[84:85] op_sel_hi:[0,1]
	v_pk_mul_f32 v[94:95], v[98:99], v[94:95]
	v_pk_mul_f32 v[90:91], v[90:91], v[84:85]
	v_mad_i64_i32 v[88:89], s[36:37], s15, v215, v[88:89]
	v_cvt_pk_bf16_f32 v84, v92, v93
	v_cvt_pk_bf16_f32 v85, v94, v95
	v_cvt_pk_bf16_f32 v87, v90, v91
	v_lshl_add_u64 v[88:89], v[88:89], 0, v[118:119]
	s_cmp_eq_u32 s100, 2
	s_cbranch_scc1 .Lht_st2
	global_store_dwordx4 v[88:89], v[84:87], off
.Lht_st2:
	v_pk_mul_f32 v[66:67], v[62:63], v[66:67]
	v_pk_mul_f32 v[58:59], v[54:55], v[58:59]
	v_mul_f32_e32 v85, 0xbfb8aa3b, v157
	v_mul_f32_e32 v86, v76, v85
	v_mul_f32_e32 v87, v77, v85
	v_exp_f32_e32 v86, v86
	v_exp_f32_e32 v87, v87
	v_mul_f32_e32 v84, v157, v157
	v_pk_mul_f32 v[76:77], v[76:77], v[80:81]
	v_add_f32_e32 v86, 1.0, v86
	v_add_f32_e32 v87, 1.0, v87
	v_rcp_f32_e32 v86, v86
	v_rcp_f32_e32 v87, v87
	v_mul_f32_e32 v78, v78, v85
	v_mul_f32_e32 v79, v79, v85
	v_exp_f32_e32 v78, v78
	v_pk_mul_f32 v[80:81], v[84:85], v[86:87] op_sel_hi:[0,1]
	v_pk_mul_f32 v[76:77], v[76:77], v[80:81]
	v_mul_f32_e32 v80, v68, v85
	v_mul_f32_e32 v81, v69, v85
	v_exp_f32_e32 v80, v80
	v_exp_f32_e32 v81, v81
	v_pk_mul_f32 v[68:69], v[68:69], v[72:73]
	v_exp_f32_e32 v79, v79
	v_add_f32_e32 v80, 1.0, v80
	v_add_f32_e32 v81, 1.0, v81
	v_rcp_f32_e32 v80, v80
	v_rcp_f32_e32 v81, v81
	v_add_f32_e32 v78, 1.0, v78
	v_add_f32_e32 v79, 1.0, v79
	v_rcp_f32_e32 v78, v78
	v_pk_mul_f32 v[72:73], v[84:85], v[80:81] op_sel_hi:[0,1]
	v_pk_mul_f32 v[72:73], v[68:69], v[72:73]
	v_mul_f32_e32 v68, v70, v85
	v_mul_f32_e32 v69, v71, v85
	v_exp_f32_e32 v68, v68
	v_exp_f32_e32 v69, v69
	v_rcp_f32_e32 v79, v79
	v_or_b32_e32 v80, 48, v146
	v_add_f32_e32 v68, 1.0, v68
	v_add_f32_e32 v69, 1.0, v69
	v_rcp_f32_e32 v68, v68
	v_rcp_f32_e32 v69, v69
	v_pk_mul_f32 v[78:79], v[84:85], v[78:79] op_sel_hi:[0,1]
	v_cvt_pk_bf16_f32 v70, v72, v73
	v_mad_i64_i32 v[72:73], s[36:37], v80, s35, v[116:117]
	v_pk_mul_f32 v[68:69], v[84:85], v[68:69] op_sel_hi:[0,1]
	v_pk_mul_f32 v[78:79], v[82:83], v[78:79]
	v_pk_mul_f32 v[74:75], v[74:75], v[68:69]
	v_mad_i64_i32 v[72:73], s[36:37], s15, v215, v[72:73]
	v_cvt_pk_bf16_f32 v68, v76, v77
	v_cvt_pk_bf16_f32 v69, v78, v79
	v_cvt_pk_bf16_f32 v71, v74, v75
	v_lshl_add_u64 v[72:73], v[72:73], 0, v[118:119]
	s_cmp_eq_u32 s100, 2
	s_cbranch_scc1 .Lht_st3
	global_store_dwordx4 v[72:73], v[68:71], off
.Lht_st3:
	s_nop 0
	v_add_u32_e32 v72, 0x80, v146
	v_pk_mul_f32 v[50:51], v[46:47], v[50:51]
	v_pk_mul_f32 v[42:43], v[38:39], v[42:43]
	v_pk_mul_f32 v[34:35], v[30:31], v[34:35]
	s_nop 0
	s_waitcnt lgkmcnt(0)
	v_mul_f32_e32 v73, 0xbfb8aa3b, v158
	v_mul_f32_e32 v70, v60, v73
	v_mul_f32_e32 v71, v61, v73
	v_exp_f32_e32 v70, v70
	v_exp_f32_e32 v71, v71
	v_mul_f32_e32 v158, v158, v158
	v_pk_mul_f32 v[60:61], v[60:61], v[64:65]
	v_add_f32_e32 v70, 1.0, v70
	v_add_f32_e32 v71, 1.0, v71
	v_rcp_f32_e32 v70, v70
	v_rcp_f32_e32 v71, v71
	v_mul_f32_e32 v62, v62, v73
	v_mul_f32_e32 v63, v63, v73
	v_exp_f32_e32 v62, v62
	v_pk_mul_f32 v[64:65], v[158:159], v[70:71] op_sel_hi:[0,1]
	v_pk_mul_f32 v[60:61], v[60:61], v[64:65]
	v_mul_f32_e32 v64, v52, v73
	v_mul_f32_e32 v65, v53, v73
	v_exp_f32_e32 v64, v64
	v_exp_f32_e32 v65, v65
	v_pk_mul_f32 v[52:53], v[52:53], v[56:57]
	v_exp_f32_e32 v63, v63
	v_add_f32_e32 v64, 1.0, v64
	v_add_f32_e32 v65, 1.0, v65
	v_rcp_f32_e32 v64, v64
	v_rcp_f32_e32 v65, v65
	v_add_f32_e32 v62, 1.0, v62
	v_add_f32_e32 v63, 1.0, v63
	v_rcp_f32_e32 v62, v62
	v_pk_mul_f32 v[56:57], v[158:159], v[64:65] op_sel_hi:[0,1]
	v_pk_mul_f32 v[56:57], v[52:53], v[56:57]
	v_mul_f32_e32 v52, v54, v73
	v_mul_f32_e32 v53, v55, v73
	v_exp_f32_e32 v52, v52
	v_exp_f32_e32 v53, v53
	v_rcp_f32_e32 v63, v63
	v_cvt_pk_bf16_f32 v54, v56, v57
	v_add_f32_e32 v52, 1.0, v52
	v_add_f32_e32 v53, 1.0, v53
	v_rcp_f32_e32 v52, v52
	v_rcp_f32_e32 v53, v53
	v_pk_mul_f32 v[62:63], v[158:159], v[62:63] op_sel_hi:[0,1]
	v_mad_i64_i32 v[56:57], s[36:37], v72, s35, v[116:117]
	v_pk_mul_f32 v[52:53], v[158:159], v[52:53] op_sel_hi:[0,1]
	v_pk_mul_f32 v[62:63], v[66:67], v[62:63]
	v_pk_mul_f32 v[58:59], v[58:59], v[52:53]
	v_mad_i64_i32 v[56:57], s[36:37], s15, v215, v[56:57]
	v_cvt_pk_bf16_f32 v52, v60, v61
	v_cvt_pk_bf16_f32 v53, v62, v63
	v_cvt_pk_bf16_f32 v55, v58, v59
	v_lshl_add_u64 v[56:57], v[56:57], 0, v[118:119]
	s_cmp_eq_u32 s100, 1
	s_cbranch_scc1 .Lht_st4
	global_store_dwordx4 v[56:57], v[52:55], off
.Lht_st4:
	v_pk_mul_f32 v[26:27], v[22:23], v[26:27]
	v_pk_mul_f32 v[4:5], v[8:9], v[4:5]
	v_mul_f32_e32 v53, 0xbfb8aa3b, v159
	v_mul_f32_e32 v54, v44, v53
	v_mul_f32_e32 v55, v45, v53
	v_exp_f32_e32 v54, v54
	v_exp_f32_e32 v55, v55
	v_mul_f32_e32 v52, v159, v159
	v_pk_mul_f32 v[44:45], v[44:45], v[48:49]
	v_add_f32_e32 v54, 1.0, v54
	v_add_f32_e32 v55, 1.0, v55
	v_rcp_f32_e32 v54, v54
	v_rcp_f32_e32 v55, v55
	v_mul_f32_e32 v46, v46, v53
	v_mul_f32_e32 v47, v47, v53
	v_exp_f32_e32 v46, v46
	v_pk_mul_f32 v[48:49], v[52:53], v[54:55] op_sel_hi:[0,1]
	v_pk_mul_f32 v[44:45], v[44:45], v[48:49]
	v_mul_f32_e32 v48, v36, v53
	v_mul_f32_e32 v49, v37, v53
	v_exp_f32_e32 v48, v48
	v_exp_f32_e32 v49, v49
	v_pk_mul_f32 v[36:37], v[36:37], v[40:41]
	v_exp_f32_e32 v47, v47
	v_add_f32_e32 v48, 1.0, v48
	v_add_f32_e32 v49, 1.0, v49
	v_rcp_f32_e32 v48, v48
	v_rcp_f32_e32 v49, v49
	v_add_f32_e32 v46, 1.0, v46
	v_add_f32_e32 v47, 1.0, v47
	v_rcp_f32_e32 v46, v46
	v_pk_mul_f32 v[40:41], v[52:53], v[48:49] op_sel_hi:[0,1]
	v_pk_mul_f32 v[40:41], v[36:37], v[40:41]
	v_mul_f32_e32 v36, v38, v53
	v_mul_f32_e32 v37, v39, v53
	v_exp_f32_e32 v36, v36
	v_exp_f32_e32 v37, v37
	v_rcp_f32_e32 v47, v47
	v_add_u32_e32 v48, 0x90, v146
	v_add_f32_e32 v36, 1.0, v36
	v_add_f32_e32 v37, 1.0, v37
	v_rcp_f32_e32 v36, v36
	v_rcp_f32_e32 v37, v37
	v_pk_mul_f32 v[46:47], v[52:53], v[46:47] op_sel_hi:[0,1]
	v_cvt_pk_bf16_f32 v38, v40, v41
	v_mad_i64_i32 v[40:41], s[36:37], v48, s35, v[116:117]
	v_pk_mul_f32 v[36:37], v[52:53], v[36:37] op_sel_hi:[0,1]
	v_pk_mul_f32 v[46:47], v[50:51], v[46:47]
	v_pk_mul_f32 v[42:43], v[42:43], v[36:37]
	v_mad_i64_i32 v[40:41], s[36:37], s15, v215, v[40:41]
	v_cvt_pk_bf16_f32 v36, v44, v45
	v_cvt_pk_bf16_f32 v37, v46, v47
	v_cvt_pk_bf16_f32 v39, v42, v43
	v_lshl_add_u64 v[40:41], v[40:41], 0, v[118:119]
	s_cmp_eq_u32 s100, 1
	s_cbranch_scc1 .Lht_st5
	global_store_dwordx4 v[40:41], v[36:39], off
.Lht_st5:
	ds_read2_b32 v[36:37], v147 offset0:160 offset1:176
	v_pk_mul_f32 v[18:19], v[14:15], v[18:19]
	v_pk_mul_f32 v[6:7], v[10:11], v[6:7]
	s_waitcnt lgkmcnt(0)
	s_andn2_b64 vcc, exec, s[6:7]
	s_waitcnt lgkmcnt(0)
	v_mul_f32_e32 v40, 0xbfb8aa3b, v36
	v_mul_f32_e32 v38, v28, v40
	v_mul_f32_e32 v39, v29, v40
	v_exp_f32_e32 v38, v38
	v_exp_f32_e32 v39, v39
	v_mul_f32_e32 v36, v36, v36
	v_pk_mul_f32 v[28:29], v[28:29], v[32:33]
	v_add_f32_e32 v38, 1.0, v38
	v_add_f32_e32 v39, 1.0, v39
	v_rcp_f32_e32 v38, v38
	v_rcp_f32_e32 v39, v39
	v_mul_f32_e32 v30, v30, v40
	v_mul_f32_e32 v31, v31, v40
	v_exp_f32_e32 v30, v30
	v_pk_mul_f32 v[32:33], v[36:37], v[38:39] op_sel_hi:[0,1]
	v_pk_mul_f32 v[28:29], v[28:29], v[32:33]
	v_mul_f32_e32 v32, v20, v40
	v_mul_f32_e32 v33, v21, v40
	v_exp_f32_e32 v32, v32
	v_exp_f32_e32 v33, v33
	v_pk_mul_f32 v[20:21], v[20:21], v[24:25]
	v_exp_f32_e32 v31, v31
	v_add_f32_e32 v32, 1.0, v32
	v_add_f32_e32 v33, 1.0, v33
	v_rcp_f32_e32 v32, v32
	v_rcp_f32_e32 v33, v33
	v_add_f32_e32 v30, 1.0, v30
	v_add_f32_e32 v31, 1.0, v31
	v_rcp_f32_e32 v30, v30
	v_pk_mul_f32 v[24:25], v[36:37], v[32:33] op_sel_hi:[0,1]
	v_pk_mul_f32 v[24:25], v[20:21], v[24:25]
	v_mul_f32_e32 v20, v22, v40
	v_mul_f32_e32 v21, v23, v40
	v_exp_f32_e32 v20, v20
	v_exp_f32_e32 v21, v21
	v_rcp_f32_e32 v31, v31
	v_add_u32_e32 v32, 0xa0, v146
	v_add_f32_e32 v20, 1.0, v20
	v_add_f32_e32 v21, 1.0, v21
	v_rcp_f32_e32 v20, v20
	v_rcp_f32_e32 v21, v21
	v_pk_mul_f32 v[30:31], v[36:37], v[30:31] op_sel_hi:[0,1]
	v_cvt_pk_bf16_f32 v22, v24, v25
	v_mad_i64_i32 v[24:25], s[36:37], v32, s35, v[116:117]
	v_pk_mul_f32 v[20:21], v[36:37], v[20:21] op_sel_hi:[0,1]
	v_pk_mul_f32 v[30:31], v[34:35], v[30:31]
	v_pk_mul_f32 v[26:27], v[26:27], v[20:21]
	v_mad_i64_i32 v[24:25], s[36:37], s15, v215, v[24:25]
	v_cvt_pk_bf16_f32 v20, v28, v29
	v_cvt_pk_bf16_f32 v21, v30, v31
	v_cvt_pk_bf16_f32 v23, v26, v27
	v_lshl_add_u64 v[24:25], v[24:25], 0, v[118:119]
	s_cmp_eq_u32 s100, 1
	s_cbranch_scc1 .Lht_st6
	global_store_dwordx4 v[24:25], v[20:23], off
.Lht_st6:
	s_nop 1
	v_mul_f32_e32 v21, 0xbfb8aa3b, v37
	v_mul_f32_e32 v22, v12, v21
	v_mul_f32_e32 v23, v13, v21
	v_exp_f32_e32 v22, v22
	v_exp_f32_e32 v23, v23
	v_mul_f32_e32 v20, v37, v37
	v_pk_mul_f32 v[12:13], v[12:13], v[16:17]
	v_add_f32_e32 v22, 1.0, v22
	v_add_f32_e32 v23, 1.0, v23
	v_rcp_f32_e32 v22, v22
	v_rcp_f32_e32 v23, v23
	v_mul_f32_e32 v14, v14, v21
	v_mul_f32_e32 v15, v15, v21
	v_exp_f32_e32 v14, v14
	v_pk_mul_f32 v[16:17], v[20:21], v[22:23] op_sel_hi:[0,1]
	v_pk_mul_f32 v[12:13], v[12:13], v[16:17]
	v_mul_f32_e32 v16, v8, v21
	v_mul_f32_e32 v17, v9, v21
	v_exp_f32_e32 v16, v16
	v_exp_f32_e32 v17, v17
	v_exp_f32_e32 v15, v15
	v_add_f32_e32 v14, 1.0, v14
	v_add_f32_e32 v16, 1.0, v16
	v_add_f32_e32 v17, 1.0, v17
	v_rcp_f32_e32 v16, v16
	v_rcp_f32_e32 v17, v17
	v_add_f32_e32 v15, 1.0, v15
	v_rcp_f32_e32 v14, v14
	v_rcp_f32_e32 v15, v15
	v_pk_mul_f32 v[8:9], v[20:21], v[16:17] op_sel_hi:[0,1]
	v_pk_mul_f32 v[8:9], v[4:5], v[8:9]
	v_mul_f32_e32 v4, v10, v21
	v_mul_f32_e32 v5, v11, v21
	v_exp_f32_e32 v4, v4
	v_exp_f32_e32 v5, v5
	v_add_u32_e32 v16, 0xb0, v146
	v_pk_mul_f32 v[14:15], v[20:21], v[14:15] op_sel_hi:[0,1]
	v_add_f32_e32 v4, 1.0, v4
	v_add_f32_e32 v5, 1.0, v5
	v_rcp_f32_e32 v4, v4
	v_rcp_f32_e32 v5, v5
	v_pk_mul_f32 v[14:15], v[18:19], v[14:15]
	v_pk_mul_f32 v[4:5], v[20:21], v[4:5] op_sel_hi:[0,1]
	v_pk_mul_f32 v[10:11], v[6:7], v[4:5]
	v_cvt_pk_bf16_f32 v6, v8, v9
	v_mad_i64_i32 v[8:9], s[36:37], v16, s35, v[116:117]
	v_mad_i64_i32 v[8:9], s[36:37], s15, v215, v[8:9]
	v_cvt_pk_bf16_f32 v4, v12, v13
	v_cvt_pk_bf16_f32 v5, v14, v15
	v_cvt_pk_bf16_f32 v7, v10, v11
	v_lshl_add_u64 v[8:9], v[8:9], 0, v[118:119]
	s_mov_b64 s[36:37], -1
	s_cmp_eq_u32 s100, 1
	s_cbranch_scc1 .Lht_st7
	global_store_dwordx4 v[8:9], v[4:7], off
.Lht_st7:
	s_cbranch_vccnz .LBB0_37
	s_andn2_b64 vcc, exec, s[8:9]
	s_cbranch_vccnz .LBB0_36
	s_barrier
	s_branch .LBB0_36
